# E10 + back-edge rotation in the mixer C loop: post-barrier slot-rotation and pointer-advance block moved in front of the step-end wait+barrier
# speedup vs baseline: 1.0031x; 1.0028x over previous
; #define WAIT_BAR(N) asm volatile("s_waitcnt vmcnt(" #N ") lgkmcnt(0)\n\ts_barrier" ::: "memory")
;   #define RESC() do { } while (0)
;   #define ROT() do { sl_prev = sl_cur; sl_cur = sl_next; sl_next = (sl_next == (NSLOT - 1) * SLOTB) ? 0 : sl_next + SLOTB; } while (0)
; template <int THRL> __device__ __forceinline__ void attn_unit(const int tid, const float mfix, int q0, int NT, const bf16* Qh, const bf16* __restrict__ Kh, const bf16* __restrict__ Vh, const bf16* Zh, bf16* Oh, const long PQ, const long PO, char* shm) {
;     ...
;   int t = 1;
;   for (; t + 5 < NT; t += 2) {
;     STEP(pB0, pB1, pA0, pA1, t, true, true, true);     WAIT_BAR(2); RESC(); ROT();
.LBB0_388:
	s_mov_b32 s14, s23
	s_mov_b32 s15, s22
	v_add_u32_e32 v188, s24, v244
	ds_read_b64_tr_b16 v[234:235], v188 offset:24576
	ds_read_b64_tr_b16 v[236:237], v188 offset:25088
	v_add_f32_e32 v100, v80, v81
	v_add_f32_e32 v100, v82, v100
	v_add_f32_e32 v100, v83, v100
	v_add_f32_e32 v100, v84, v100
	v_add_f32_e32 v100, v85, v100
	v_cvt_pk_bf16_f32 v160, v80, v81
	v_cvt_pk_bf16_f32 v161, v82, v83
	s_waitcnt lgkmcnt(9)
	v_mfma_f32_32x32x16_bf16 v[112:127], v[96:99], v[172:175], v[48:63]
	ds_read_b64_tr_b16 v[80:81], v188 offset:28672
	ds_read_b64_tr_b16 v[82:83], v188 offset:29184
	v_add_f32_e32 v96, v86, v100
	v_add_f32_e32 v96, v87, v96
	v_add_f32_e32 v96, v88, v96
	v_add_f32_e32 v144, v89, v96
	s_waitcnt lgkmcnt(10)
	v_mfma_f32_32x32x16_bf16 v[96:111], v[180:183], v[172:175], v[48:63]
	v_cvt_pk_bf16_f32 v162, v84, v85
	v_cvt_pk_bf16_f32 v163, v86, v87
	ds_read_b64_tr_b16 v[84:85], v188 offset:25600
	ds_read_b64_tr_b16 v[86:87], v188 offset:26112
	v_add_f32_e32 v144, v90, v144
	v_add_f32_e32 v144, v91, v144
	v_add_f32_e32 v144, v92, v144
	v_add_f32_e32 v144, v93, v144
	v_cvt_pk_bf16_f32 v156, v88, v89
	v_cvt_pk_bf16_f32 v157, v90, v91
	s_waitcnt lgkmcnt(11)
	v_mfma_f32_32x32x16_bf16 v[112:127], v[184:187], v[168:171], v[112:127]
	ds_read_b64_tr_b16 v[88:89], v188 offset:29696
	ds_read_b64_tr_b16 v[90:91], v188 offset:30208
	s_waitcnt lgkmcnt(12)
	v_mfma_f32_32x32x16_bf16 v[96:111], v[176:179], v[168:171], v[96:111]
	v_add_f32_e32 v144, v94, v144
	v_add_f32_e32 v144, v95, v144
	v_add_f32_e32 v144, v64, v144
	v_add_f32_e32 v144, v65, v144
	v_cvt_pk_bf16_f32 v158, v92, v93
	v_cvt_pk_bf16_f32 v159, v94, v95
	ds_read_b64_tr_b16 v[92:93], v188 offset:26624
	ds_read_b64_tr_b16 v[94:95], v188 offset:27136
	s_waitcnt lgkmcnt(13)
	v_mfma_f32_32x32x16_bf16 v[112:127], v[140:143], v[164:167], v[112:127]
	v_add_f32_e32 v140, v66, v144
	v_add_f32_e32 v140, v67, v140
	v_add_f32_e32 v140, v68, v140
	v_add_f32_e32 v140, v69, v140
	v_cvt_pk_bf16_f32 v148, v64, v65
	v_cvt_pk_bf16_f32 v149, v66, v67
	ds_read_b64_tr_b16 v[64:65], v188 offset:30720
	ds_read_b64_tr_b16 v[66:67], v188 offset:31232
	s_waitcnt lgkmcnt(14)
	v_mfma_f32_32x32x16_bf16 v[96:111], v[136:139], v[164:167], v[96:111]
	v_add_f32_e32 v136, v70, v140
	v_add_f32_e32 v136, v71, v136
	v_add_f32_e32 v136, v72, v136
	v_add_f32_e32 v136, v73, v136
	v_cvt_pk_bf16_f32 v150, v68, v69
	v_cvt_pk_bf16_f32 v151, v70, v71
	ds_read_b64_tr_b16 v[68:69], v188 offset:27648
	ds_read_b64_tr_b16 v[70:71], v188 offset:28160
	s_waitcnt lgkmcnt(14)
	v_mfma_f32_32x32x16_bf16 v[112:127], v[132:135], v[152:155], v[112:127]
	v_add_f32_e32 v132, v74, v136
	v_add_f32_e32 v132, v75, v132
	v_add_f32_e32 v132, v76, v132
	v_add_f32_e32 v132, v77, v132
	v_cvt_pk_bf16_f32 v144, v72, v73
	v_cvt_pk_bf16_f32 v145, v74, v75
	ds_read_b64_tr_b16 v[72:73], v188 offset:31744
	ds_read_b64_tr_b16 v[74:75], v188 offset:32256
	v_mfma_f32_32x32x16_bf16 v[96:111], v[128:131], v[152:155], v[96:111]
	v_add_f32_e32 v128, v78, v132
	v_add_f32_e32 v128, v79, v128
	v_add_f32_e32 v128, 0, v128
	v_cvt_pk_bf16_f32 v146, v76, v77
	v_cvt_pk_bf16_f32 v147, v78, v79
	v_lshl_add_u64 v[76:77], v[224:225], 0, s[90:91]
	s_add_i32 s16, s22, s19
	s_mov_b32 s17, m0
	s_mov_b32 m0, s16
	s_nop 0
	global_load_lds_dwordx4 v[76:77], off
	s_mov_b32 m0, s17
	v_lshl_add_u64 v[76:77], v[226:227], 0, s[86:87]
	s_add_i32 s16, s23, s18
	s_mov_b32 s17, m0
	s_mov_b32 m0, s16
	s_nop 0
	global_load_lds_dwordx4 v[76:77], off
	s_mov_b32 m0, s17
	v_add_f32_e32 v188, v219, v128
	s_waitcnt lgkmcnt(14)
	v_mfma_f32_32x32x16_bf16 v[16:31], v[160:163], v[234:237], v[16:31]
	v_exp_f32_e32 v112, v112
	v_exp_f32_e32 v113, v113
	v_exp_f32_e32 v114, v114
	v_exp_f32_e32 v115, v115
	s_waitcnt lgkmcnt(12)
	v_mfma_f32_32x32x16_bf16 v[32:47], v[160:163], v[80:83], v[32:47]
	v_exp_f32_e32 v116, v116
	v_exp_f32_e32 v117, v117
	v_exp_f32_e32 v118, v118
	v_exp_f32_e32 v119, v119
	v_add_u32_e32 v80, s14, v242
	ds_read_b128 v[76:79], v80
	ds_read_b128 v[132:135], v80 offset:512
	s_waitcnt lgkmcnt(12)
	v_mfma_f32_32x32x16_bf16 v[16:31], v[156:159], v[84:87], v[16:31]
	v_exp_f32_e32 v120, v120
	v_exp_f32_e32 v121, v121
	v_exp_f32_e32 v122, v122
	v_exp_f32_e32 v123, v123
	ds_read_b128 v[136:139], v80 offset:2048
	ds_read_b128 v[140:143], v80 offset:2560
	s_waitcnt lgkmcnt(12)
	v_mfma_f32_32x32x16_bf16 v[32:47], v[156:159], v[88:91], v[32:47]
	v_exp_f32_e32 v124, v124
	v_exp_f32_e32 v125, v125
	v_exp_f32_e32 v126, v126
	v_exp_f32_e32 v127, v127
	ds_read_b128 v[176:179], v80 offset:4096
	ds_read_b128 v[180:183], v80 offset:4608
	s_waitcnt lgkmcnt(12)
	v_mfma_f32_32x32x16_bf16 v[16:31], v[148:151], v[92:95], v[16:31]
	v_exp_f32_e32 v96, v96
	v_exp_f32_e32 v97, v97
	v_exp_f32_e32 v98, v98
	v_exp_f32_e32 v99, v99
	ds_read_b128 v[184:187], v80 offset:6144
	ds_read_b128 v[128:131], v80 offset:6656
	s_waitcnt lgkmcnt(12)
	v_mfma_f32_32x32x16_bf16 v[32:47], v[148:151], v[64:67], v[32:47]
	v_exp_f32_e32 v100, v100
	v_exp_f32_e32 v101, v101
	v_exp_f32_e32 v102, v102
	v_exp_f32_e32 v103, v103
	s_waitcnt lgkmcnt(10)
	v_mfma_f32_32x32x16_bf16 v[16:31], v[144:147], v[68:71], v[16:31]
	v_exp_f32_e32 v104, v104
	v_exp_f32_e32 v105, v105
	v_exp_f32_e32 v106, v106
	v_exp_f32_e32 v107, v107
	s_waitcnt lgkmcnt(8)
	v_mfma_f32_32x32x16_bf16 v[32:47], v[144:147], v[72:75], v[32:47]
	v_exp_f32_e32 v108, v108
	v_exp_f32_e32 v109, v109
	v_exp_f32_e32 v110, v110
	v_exp_f32_e32 v111, v111
	s_add_i32 s16, s23, 0x2000
	s_cmpk_lg_i32 s23, 0x4000
	s_cselect_b32 s22, s16, 0
	s_waitcnt vmcnt(2) lgkmcnt(0)
	s_barrier
; #define WAIT_BAR(N) asm volatile("s_waitcnt vmcnt(" #N ") lgkmcnt(0)\n\ts_barrier" ::: "memory")
;   #define RESC() do { } while (0)
;   #define ROT() do { sl_prev = sl_cur; sl_cur = sl_next; sl_next = (sl_next == (NSLOT - 1) * SLOTB) ? 0 : sl_next + SLOTB; } while (0)
; template <int THRL> __device__ __forceinline__ void attn_unit(const int tid, const float mfix, int q0, int NT, const bf16* Qh, const bf16* __restrict__ Kh, const bf16* __restrict__ Vh, const bf16* Zh, bf16* Oh, const long PQ, const long PO, char* shm) {
;     ...
;   int t = 1;
;   for (; t + 5 < NT; t += 2) {
;     STEP(pB0, pB1, pA0, pA1, t, true, true, true);     WAIT_BAR(2); RESC(); ROT();
;     STEP(pA0, pA1, pB0, pB1, t + 1, true, true, true); WAIT_BAR(2); RESC(); ROT();
	v_add_u32_e32 v219, s15, v244
	ds_read_b64_tr_b16 v[234:235], v219 offset:24576
	ds_read_b64_tr_b16 v[236:237], v219 offset:25088
	s_waitcnt lgkmcnt(9)
	v_mfma_f32_32x32x16_bf16 v[80:95], v[76:79], v[172:175], v[48:63]
	v_add_f32_e32 v64, v112, v113
	v_add_f32_e32 v64, v114, v64
	v_add_f32_e32 v64, v115, v64
	v_add_f32_e32 v64, v116, v64
	v_add_f32_e32 v64, v117, v64
	v_cvt_pk_bf16_f32 v160, v112, v113
	v_cvt_pk_bf16_f32 v161, v114, v115
	ds_read_b64_tr_b16 v[112:113], v219 offset:28672
	ds_read_b64_tr_b16 v[114:115], v219 offset:29184
	v_add_f32_e32 v64, v118, v64
	v_add_f32_e32 v64, v119, v64
	v_add_f32_e32 v64, v120, v64
	v_add_f32_e32 v144, v121, v64
	s_waitcnt lgkmcnt(10)
	v_mfma_f32_32x32x16_bf16 v[64:79], v[132:135], v[172:175], v[48:63]
	v_cvt_pk_bf16_f32 v162, v116, v117
	v_cvt_pk_bf16_f32 v163, v118, v119
	ds_read_b64_tr_b16 v[116:117], v219 offset:25600
	ds_read_b64_tr_b16 v[118:119], v219 offset:26112
	s_waitcnt lgkmcnt(11)
	v_mfma_f32_32x32x16_bf16 v[80:95], v[136:139], v[168:171], v[80:95]
	v_add_f32_e32 v132, v122, v144
	v_add_f32_e32 v132, v123, v132
	v_add_f32_e32 v132, v124, v132
	v_add_f32_e32 v132, v125, v132
	v_cvt_pk_bf16_f32 v156, v120, v121
	v_cvt_pk_bf16_f32 v157, v122, v123
	ds_read_b64_tr_b16 v[120:121], v219 offset:29696
	ds_read_b64_tr_b16 v[122:123], v219 offset:30208
	s_waitcnt lgkmcnt(12)
	v_mfma_f32_32x32x16_bf16 v[64:79], v[140:143], v[168:171], v[64:79]
	v_add_f32_e32 v132, v126, v132
	v_add_f32_e32 v132, v127, v132
	v_add_f32_e32 v132, v96, v132
	v_add_f32_e32 v132, v97, v132
	v_cvt_pk_bf16_f32 v158, v124, v125
	v_cvt_pk_bf16_f32 v159, v126, v127
	ds_read_b64_tr_b16 v[124:125], v219 offset:26624
	ds_read_b64_tr_b16 v[126:127], v219 offset:27136
	s_waitcnt lgkmcnt(13)
	v_mfma_f32_32x32x16_bf16 v[80:95], v[176:179], v[164:167], v[80:95]
	v_add_f32_e32 v132, v98, v132
	v_add_f32_e32 v132, v99, v132
	v_add_f32_e32 v132, v100, v132
	v_add_f32_e32 v132, v101, v132
	v_cvt_pk_bf16_f32 v148, v96, v97
	v_cvt_pk_bf16_f32 v149, v98, v99
	ds_read_b64_tr_b16 v[228:229], v219 offset:30720
	ds_read_b64_tr_b16 v[230:231], v219 offset:31232
	s_waitcnt lgkmcnt(14)
	v_mfma_f32_32x32x16_bf16 v[64:79], v[180:183], v[164:167], v[64:79]
	v_add_f32_e32 v96, v102, v132
	v_add_f32_e32 v96, v103, v96
	v_add_f32_e32 v96, v104, v96
	v_add_f32_e32 v96, v105, v96
	v_cvt_pk_bf16_f32 v150, v100, v101
	v_cvt_pk_bf16_f32 v151, v102, v103
	ds_read_b64_tr_b16 v[100:101], v219 offset:27648
	ds_read_b64_tr_b16 v[102:103], v219 offset:28160
	s_waitcnt lgkmcnt(14)
	v_mfma_f32_32x32x16_bf16 v[80:95], v[184:187], v[152:155], v[80:95]
	v_add_f32_e32 v96, v106, v96
	v_add_f32_e32 v96, v107, v96
	v_add_f32_e32 v96, v108, v96
	v_add_f32_e32 v96, v109, v96
	v_cvt_pk_bf16_f32 v144, v104, v105
	v_cvt_pk_bf16_f32 v145, v106, v107
	ds_read_b64_tr_b16 v[104:105], v219 offset:31744
	ds_read_b64_tr_b16 v[106:107], v219 offset:32256
	v_mfma_f32_32x32x16_bf16 v[64:79], v[128:131], v[152:155], v[64:79]
	v_add_f32_e32 v96, v110, v96
	v_add_f32_e32 v96, v111, v96
	v_add_f32_e32 v96, 0, v96
	v_cvt_pk_bf16_f32 v146, v108, v109
	v_cvt_pk_bf16_f32 v147, v110, v111
	s_mov_b64 s[16:17], 0x348000
	v_add_f32_e32 v219, v188, v96
	v_lshl_add_u64 v[96:97], v[224:225], 0, s[16:17]
	s_add_i32 s15, s23, s19
	s_mov_b32 s16, m0
	s_mov_b32 m0, s15
	s_nop 0
	global_load_lds_dwordx4 v[96:97], off
	s_mov_b32 m0, s16
	v_lshl_add_u64 v[226:227], v[226:227], 0, s[88:89]
	s_add_i32 s15, s22, s18
	s_mov_b32 s16, m0
	s_mov_b32 m0, s15
	s_nop 0
	global_load_lds_dwordx4 v[226:227], off
	s_mov_b32 m0, s16
	s_waitcnt lgkmcnt(14)
	v_mfma_f32_32x32x16_bf16 v[16:31], v[160:163], v[234:237], v[16:31]
	v_exp_f32_e32 v80, v80
	v_exp_f32_e32 v81, v81
	v_exp_f32_e32 v82, v82
	v_exp_f32_e32 v83, v83
	s_waitcnt lgkmcnt(12)
	v_mfma_f32_32x32x16_bf16 v[32:47], v[160:163], v[112:115], v[32:47]
	v_exp_f32_e32 v84, v84
	v_exp_f32_e32 v85, v85
	v_exp_f32_e32 v86, v86
	v_exp_f32_e32 v87, v87
	v_add_u32_e32 v108, s22, v242
	ds_read_b128 v[96:99], v108
	ds_read_b128 v[180:183], v108 offset:512
	s_waitcnt lgkmcnt(12)
	v_mfma_f32_32x32x16_bf16 v[16:31], v[156:159], v[116:119], v[16:31]
	v_exp_f32_e32 v88, v88
	v_exp_f32_e32 v89, v89
	v_exp_f32_e32 v90, v90
	v_exp_f32_e32 v91, v91
	ds_read_b128 v[184:187], v108 offset:2048
	ds_read_b128 v[176:179], v108 offset:2560
	s_waitcnt lgkmcnt(12)
	v_mfma_f32_32x32x16_bf16 v[32:47], v[156:159], v[120:123], v[32:47]
	v_exp_f32_e32 v92, v92
	v_exp_f32_e32 v93, v93
	v_exp_f32_e32 v94, v94
	v_exp_f32_e32 v95, v95
	ds_read_b128 v[140:143], v108 offset:4096
	ds_read_b128 v[136:139], v108 offset:4608
	s_waitcnt lgkmcnt(12)
	v_mfma_f32_32x32x16_bf16 v[16:31], v[148:151], v[124:127], v[16:31]
	v_exp_f32_e32 v64, v64
	v_exp_f32_e32 v65, v65
	v_exp_f32_e32 v66, v66
	v_exp_f32_e32 v67, v67
	ds_read_b128 v[132:135], v108 offset:6144
	ds_read_b128 v[128:131], v108 offset:6656
	s_waitcnt lgkmcnt(12)
	v_mfma_f32_32x32x16_bf16 v[32:47], v[148:151], v[228:231], v[32:47]
	v_exp_f32_e32 v68, v68
	v_exp_f32_e32 v69, v69
	v_exp_f32_e32 v70, v70
	v_exp_f32_e32 v71, v71
	s_waitcnt lgkmcnt(10)
	v_mfma_f32_32x32x16_bf16 v[16:31], v[144:147], v[100:103], v[16:31]
	v_exp_f32_e32 v72, v72
	v_exp_f32_e32 v73, v73
	v_exp_f32_e32 v74, v74
	v_exp_f32_e32 v75, v75
	s_waitcnt lgkmcnt(8)
	v_mfma_f32_32x32x16_bf16 v[32:47], v[144:147], v[104:107], v[32:47]
	v_exp_f32_e32 v76, v76
	v_exp_f32_e32 v77, v77
	v_exp_f32_e32 v78, v78
	v_exp_f32_e32 v79, v79
	s_add_i32 s15, s22, 0x2000
	s_cmpk_lg_i32 s22, 0x4000
	s_cselect_b32 s23, s15, 0
	s_add_i32 s21, s21, 2
	v_lshl_add_u64 v[224:225], v[224:225], 0, s[88:89]
	s_cmpk_gt_u32 s21, 0xf8
	s_mov_b32 s24, s14
	s_waitcnt vmcnt(2) lgkmcnt(0)
	s_barrier
	s_cbranch_scc0 .LBB0_388
; #define WAIT_BAR(N) asm volatile("s_waitcnt vmcnt(" #N ") lgkmcnt(0)\n\ts_barrier" ::: "memory")
;   #define RESC() do { } while (0)
;   #define ROT() do { sl_prev = sl_cur; sl_cur = sl_next; sl_next = (sl_next == (NSLOT - 1) * SLOTB) ? 0 : sl_next + SLOTB; } while (0)
;   #define ENDW(tt) do { if ((tt) + 3 < NT) { WAIT_BAR(2); } else if ((tt) + 2 < NT) { WAIT_BAR(1); } else { WAIT_BAR(0); } } while (0)
; template <int THRL> __device__ __forceinline__ void attn_unit(const int tid, const float mfix, int q0, int NT, const bf16* Qh, const bf16* __restrict__ Kh, const bf16* __restrict__ Vh, const bf16* Zh, bf16* Oh, const long PQ, const long PO, char* shm) {
;     ...
;   int t = 1;
;   for (; t + 5 < NT; t += 2) {
;     STEP(pB0, pB1, pA0, pA1, t, true, true, true);     WAIT_BAR(2); RESC(); ROT();
;     STEP(pA0, pA1, pB0, pB1, t + 1, true, true, true); WAIT_BAR(2); RESC(); ROT();
;   }
;     ...
;   for (; t + 1 < NT; t += 2) {
;     STEP(pB0, pB1, pA0, pA1, t, (t + 3 < NT), (t + 1 < NT), (t + 1 < NT));         ENDW(t);     RESC(); ROT();
;     STEP(pA0, pA1, pB0, pB1, t + 1, (t + 4 < NT), (t + 2 < NT), (t + 2 < NT));     ENDW(t + 1); RESC(); ROT();
	s_and_b32 s15, s20, 0x3fffffc0
	s_lshl_b32 s15, s15, 2
	s_add_i32 s16, s15, 0
	v_add_u32_e32 v188, s14, v244
	ds_read_b64_tr_b16 v[224:225], v188 offset:24576
	ds_read_b64_tr_b16 v[226:227], v188 offset:25088
	v_add_f32_e32 v100, v80, v81
	v_add_f32_e32 v100, v82, v100
	v_add_f32_e32 v100, v83, v100
	v_add_f32_e32 v100, v84, v100
	v_add_f32_e32 v100, v85, v100
	v_cvt_pk_bf16_f32 v160, v80, v81
	v_cvt_pk_bf16_f32 v161, v82, v83
	s_waitcnt lgkmcnt(9)
	v_mfma_f32_32x32x16_bf16 v[112:127], v[96:99], v[172:175], v[48:63]
	ds_read_b64_tr_b16 v[80:81], v188 offset:28672
	ds_read_b64_tr_b16 v[82:83], v188 offset:29184
	v_add_f32_e32 v96, v86, v100
	v_add_f32_e32 v96, v87, v96
	v_add_f32_e32 v96, v88, v96
	v_add_f32_e32 v144, v89, v96
	v_cvt_pk_bf16_f32 v162, v84, v85
	v_cvt_pk_bf16_f32 v163, v86, v87
	s_waitcnt lgkmcnt(10)
	v_mfma_f32_32x32x16_bf16 v[96:111], v[180:183], v[172:175], v[48:63]
	ds_read_b64_tr_b16 v[84:85], v188 offset:25600
	ds_read_b64_tr_b16 v[86:87], v188 offset:26112
	v_add_f32_e32 v144, v90, v144
	v_add_f32_e32 v144, v91, v144
	v_add_f32_e32 v144, v92, v144
	v_add_f32_e32 v144, v93, v144
	v_cvt_pk_bf16_f32 v156, v88, v89
	v_cvt_pk_bf16_f32 v157, v90, v91
	s_waitcnt lgkmcnt(11)
	v_mfma_f32_32x32x16_bf16 v[112:127], v[184:187], v[168:171], v[112:127]
	ds_read_b64_tr_b16 v[88:89], v188 offset:29696
	ds_read_b64_tr_b16 v[90:91], v188 offset:30208
	v_add_f32_e32 v144, v94, v144
	v_add_f32_e32 v144, v95, v144
	v_add_f32_e32 v144, v64, v144
	v_add_f32_e32 v144, v65, v144
	v_cvt_pk_bf16_f32 v158, v92, v93
	v_cvt_pk_bf16_f32 v159, v94, v95
	s_waitcnt lgkmcnt(12)
	v_mfma_f32_32x32x16_bf16 v[96:111], v[176:179], v[168:171], v[96:111]
	ds_read_b64_tr_b16 v[92:93], v188 offset:26624
	ds_read_b64_tr_b16 v[94:95], v188 offset:27136
	s_waitcnt lgkmcnt(13)
	v_mfma_f32_32x32x16_bf16 v[112:127], v[140:143], v[164:167], v[112:127]
	v_add_f32_e32 v140, v66, v144
	v_add_f32_e32 v140, v67, v140
	v_add_f32_e32 v140, v68, v140
	v_add_f32_e32 v140, v69, v140
	v_cvt_pk_bf16_f32 v148, v64, v65
	v_cvt_pk_bf16_f32 v149, v66, v67
	ds_read_b64_tr_b16 v[64:65], v188 offset:30720
	ds_read_b64_tr_b16 v[66:67], v188 offset:31232
	s_waitcnt lgkmcnt(14)
	v_mfma_f32_32x32x16_bf16 v[96:111], v[136:139], v[164:167], v[96:111]
	v_add_f32_e32 v136, v70, v140
	v_add_f32_e32 v136, v71, v136
	v_add_f32_e32 v136, v72, v136
	v_add_f32_e32 v136, v73, v136
	v_cvt_pk_bf16_f32 v150, v68, v69
	v_cvt_pk_bf16_f32 v151, v70, v71
	ds_read_b64_tr_b16 v[68:69], v188 offset:27648
	ds_read_b64_tr_b16 v[70:71], v188 offset:28160
	s_waitcnt lgkmcnt(14)
	v_mfma_f32_32x32x16_bf16 v[112:127], v[132:135], v[152:155], v[112:127]
	v_add_f32_e32 v132, v74, v136
	v_add_f32_e32 v132, v75, v132
	v_add_f32_e32 v132, v76, v132
	v_add_f32_e32 v132, v77, v132
	v_cvt_pk_bf16_f32 v144, v72, v73
	v_cvt_pk_bf16_f32 v145, v74, v75
	ds_read_b64_tr_b16 v[72:73], v188 offset:31744
	ds_read_b64_tr_b16 v[74:75], v188 offset:32256
	v_mfma_f32_32x32x16_bf16 v[96:111], v[128:131], v[152:155], v[96:111]
	v_add_f32_e32 v128, v78, v132
	v_add_f32_e32 v128, v79, v128
	v_add_f32_e32 v128, 0, v128
	v_cvt_pk_bf16_f32 v146, v76, v77
	v_cvt_pk_bf16_f32 v147, v78, v79
	s_add_i32 s14, s22, s19
	v_lshl_add_u64 v[76:77], v[222:223], 0, s[92:93]
	s_mov_b32 s15, m0
	s_mov_b32 m0, s14
	s_nop 0
	global_load_lds_dwordx4 v[76:77], off
	s_mov_b32 m0, s15
	s_mov_b64 s[14:15], 0xceb8000
	v_lshl_add_u64 v[76:77], v[220:221], 0, s[14:15]
	s_add_i32 s14, s23, s18
	s_mov_b32 s15, m0
	s_mov_b32 m0, s14
	s_nop 0
	global_load_lds_dwordx4 v[76:77], off
	s_mov_b32 m0, s15
	v_add_f32_e32 v188, v219, v128
	s_waitcnt lgkmcnt(14)
	v_mfma_f32_32x32x16_bf16 v[16:31], v[160:163], v[224:227], v[16:31]
	v_exp_f32_e32 v112, v112
	v_exp_f32_e32 v113, v113
	v_exp_f32_e32 v114, v114
	v_exp_f32_e32 v115, v115
	s_waitcnt lgkmcnt(12)
	v_mfma_f32_32x32x16_bf16 v[32:47], v[160:163], v[80:83], v[32:47]
	v_exp_f32_e32 v116, v116
	v_exp_f32_e32 v117, v117
	v_exp_f32_e32 v118, v118
	v_exp_f32_e32 v119, v119
	v_add_u32_e32 v80, s23, v242
	ds_read_b128 v[76:79], v80
	ds_read_b128 v[176:179], v80 offset:512
	s_waitcnt lgkmcnt(12)
	v_mfma_f32_32x32x16_bf16 v[16:31], v[156:159], v[84:87], v[16:31]
	v_exp_f32_e32 v120, v120
	v_exp_f32_e32 v121, v121
	v_exp_f32_e32 v122, v122
	v_exp_f32_e32 v123, v123
	ds_read_b128 v[84:87], v80 offset:2048
	ds_read_b128 v[180:183], v80 offset:2560
	s_waitcnt lgkmcnt(12)
	v_mfma_f32_32x32x16_bf16 v[32:47], v[156:159], v[88:91], v[32:47]
	v_exp_f32_e32 v124, v124
	v_exp_f32_e32 v125, v125
	v_exp_f32_e32 v126, v126
	v_exp_f32_e32 v127, v127
	ds_read_b128 v[88:91], v80 offset:4096
	ds_read_b128 v[184:187], v80 offset:4608
	s_waitcnt lgkmcnt(12)
	v_mfma_f32_32x32x16_bf16 v[16:31], v[148:151], v[92:95], v[16:31]
	v_exp_f32_e32 v96, v96
	v_exp_f32_e32 v97, v97
	v_exp_f32_e32 v98, v98
	v_exp_f32_e32 v99, v99
	ds_read_b128 v[92:95], v80 offset:6144
	ds_read_b128 v[80:83], v80 offset:6656
	s_waitcnt lgkmcnt(12)
	v_mfma_f32_32x32x16_bf16 v[32:47], v[148:151], v[64:67], v[32:47]
	v_exp_f32_e32 v100, v100
	v_exp_f32_e32 v101, v101
	v_exp_f32_e32 v102, v102
	v_exp_f32_e32 v103, v103
	s_waitcnt lgkmcnt(10)
	v_mfma_f32_32x32x16_bf16 v[16:31], v[144:147], v[68:71], v[16:31]
	v_exp_f32_e32 v104, v104
	v_exp_f32_e32 v105, v105
	v_exp_f32_e32 v106, v106
	v_exp_f32_e32 v107, v107
	s_waitcnt lgkmcnt(8)
	v_mfma_f32_32x32x16_bf16 v[32:47], v[144:147], v[72:75], v[32:47]
	v_exp_f32_e32 v108, v108
	v_exp_f32_e32 v109, v109
	v_exp_f32_e32 v110, v110
	v_exp_f32_e32 v111, v111
	s_waitcnt vmcnt(2) lgkmcnt(0)
	s_barrier
; #define WAIT_BAR(N) asm volatile("s_waitcnt vmcnt(" #N ") lgkmcnt(0)\n\ts_barrier" ::: "memory")
;   #define RESC() do { } while (0)
;   #define ROT() do { sl_prev = sl_cur; sl_cur = sl_next; sl_next = (sl_next == (NSLOT - 1) * SLOTB) ? 0 : sl_next + SLOTB; } while (0)
;   #define ENDW(tt) do { if ((tt) + 3 < NT) { WAIT_BAR(2); } else if ((tt) + 2 < NT) { WAIT_BAR(1); } else { WAIT_BAR(0); } } while (0)
; template <int THRL> __device__ __forceinline__ void attn_unit(const int tid, const float mfix, int q0, int NT, const bf16* Qh, const bf16* __restrict__ Kh, const bf16* __restrict__ Vh, const bf16* Zh, bf16* Oh, const long PQ, const long PO, char* shm) {
;     ...
;   int t = 1;
;   for (; t + 5 < NT; t += 2) {
;     STEP(pB0, pB1, pA0, pA1, t, true, true, true);     WAIT_BAR(2); RESC(); ROT();
;     STEP(pA0, pA1, pB0, pB1, t + 1, true, true, true); WAIT_BAR(2); RESC(); ROT();
;   }
;     ...
;   for (; t + 1 < NT; t += 2) {
;     STEP(pB0, pB1, pA0, pA1, t, (t + 3 < NT), (t + 1 < NT), (t + 1 < NT));         ENDW(t);     RESC(); ROT();
;     STEP(pA0, pA1, pB0, pB1, t + 1, (t + 4 < NT), (t + 2 < NT), (t + 2 < NT));     ENDW(t + 1); RESC(); ROT();
	s_add_i32 s14, s23, 0x2000
	s_cmpk_lg_i32 s23, 0x4000
	s_cselect_b32 s15, s14, 0
	v_add_u32_e32 v219, s22, v244
	ds_read_b64_tr_b16 v[224:225], v219 offset:24576
	ds_read_b64_tr_b16 v[226:227], v219 offset:25088
	v_add_f32_e32 v64, v112, v113
	v_add_f32_e32 v64, v114, v64
	v_add_f32_e32 v64, v115, v64
	v_add_f32_e32 v64, v116, v64
	v_add_f32_e32 v64, v117, v64
	v_cvt_pk_bf16_f32 v160, v112, v113
	v_cvt_pk_bf16_f32 v161, v114, v115
	s_waitcnt lgkmcnt(9)
	v_mfma_f32_32x32x16_bf16 v[128:143], v[76:79], v[172:175], v[48:63]
	ds_read_b64_tr_b16 v[112:113], v219 offset:28672
	ds_read_b64_tr_b16 v[114:115], v219 offset:29184
	v_add_f32_e32 v64, v118, v64
	v_add_f32_e32 v64, v119, v64
	v_add_f32_e32 v64, v120, v64
	v_add_f32_e32 v144, v121, v64
	s_waitcnt lgkmcnt(10)
	v_mfma_f32_32x32x16_bf16 v[64:79], v[176:179], v[172:175], v[48:63]
	v_cvt_pk_bf16_f32 v162, v116, v117
	v_cvt_pk_bf16_f32 v163, v118, v119
	ds_read_b64_tr_b16 v[116:117], v219 offset:25600
	ds_read_b64_tr_b16 v[118:119], v219 offset:26112
	s_waitcnt lgkmcnt(11)
	v_mfma_f32_32x32x16_bf16 v[128:143], v[84:87], v[168:171], v[128:143]
	v_add_f32_e32 v84, v122, v144
	v_add_f32_e32 v84, v123, v84
	v_add_f32_e32 v84, v124, v84
	v_add_f32_e32 v144, v125, v84
	v_cvt_pk_bf16_f32 v156, v120, v121
	v_cvt_pk_bf16_f32 v157, v122, v123
	ds_read_b64_tr_b16 v[84:85], v219 offset:29696
	ds_read_b64_tr_b16 v[86:87], v219 offset:30208
	s_waitcnt lgkmcnt(12)
	v_mfma_f32_32x32x16_bf16 v[64:79], v[180:183], v[168:171], v[64:79]
	v_add_f32_e32 v120, v126, v144
	v_add_f32_e32 v120, v127, v120
	v_add_f32_e32 v120, v96, v120
	v_add_f32_e32 v144, v97, v120
	v_cvt_pk_bf16_f32 v158, v124, v125
	v_cvt_pk_bf16_f32 v159, v126, v127
	ds_read_b64_tr_b16 v[120:121], v219 offset:26624
	ds_read_b64_tr_b16 v[122:123], v219 offset:27136
	s_waitcnt lgkmcnt(13)
	v_mfma_f32_32x32x16_bf16 v[128:143], v[88:91], v[164:167], v[128:143]
	v_add_f32_e32 v88, v98, v144
	v_add_f32_e32 v88, v99, v88
	v_add_f32_e32 v88, v100, v88
	v_add_f32_e32 v124, v101, v88
	v_cvt_pk_bf16_f32 v148, v96, v97
	v_cvt_pk_bf16_f32 v149, v98, v99
	ds_read_b64_tr_b16 v[88:89], v219 offset:30720
	ds_read_b64_tr_b16 v[90:91], v219 offset:31232
	s_waitcnt lgkmcnt(14)
	v_mfma_f32_32x32x16_bf16 v[64:79], v[184:187], v[164:167], v[64:79]
	v_add_f32_e32 v96, v102, v124
	v_add_f32_e32 v96, v103, v96
	v_add_f32_e32 v96, v104, v96
	v_add_f32_e32 v96, v105, v96
	v_cvt_pk_bf16_f32 v150, v100, v101
	v_cvt_pk_bf16_f32 v151, v102, v103
	ds_read_b64_tr_b16 v[100:101], v219 offset:27648
	ds_read_b64_tr_b16 v[102:103], v219 offset:28160
	s_waitcnt lgkmcnt(14)
	v_mfma_f32_32x32x16_bf16 v[128:143], v[92:95], v[152:155], v[128:143]
	v_add_f32_e32 v92, v106, v96
	v_add_f32_e32 v92, v107, v92
	v_add_f32_e32 v92, v108, v92
	v_add_f32_e32 v96, v109, v92
	v_cvt_pk_bf16_f32 v144, v104, v105
	v_cvt_pk_bf16_f32 v145, v106, v107
	ds_read_b64_tr_b16 v[92:93], v219 offset:31744
	ds_read_b64_tr_b16 v[94:95], v219 offset:32256
	v_mfma_f32_32x32x16_bf16 v[64:79], v[80:83], v[152:155], v[64:79]
	v_add_f32_e32 v80, v110, v96
	v_add_f32_e32 v80, v111, v80
	v_add_f32_e32 v80, 0, v80
	v_cvt_pk_bf16_f32 v146, v108, v109
	v_cvt_pk_bf16_f32 v147, v110, v111
	s_nop 0
	v_add_f32_e32 v188, v188, v80
	s_add_i32 s14, s23, s19
	v_lshl_add_u64 v[80:81], v[222:223], 0, s[94:95]
	s_mov_b32 s17, m0
	s_mov_b32 m0, s14
	s_nop 0
	global_load_lds_dwordx4 v[80:81], off
	s_mov_b32 m0, s17
	s_mov_b64 s[20:21], 0xcf8a000
	s_add_i32 s14, s15, s18
	v_lshl_add_u64 v[80:81], v[220:221], 0, s[20:21]
	s_mov_b32 s17, m0
	s_mov_b32 m0, s14
	s_nop 0
	global_load_lds_dwordx4 v[80:81], off
	s_mov_b32 m0, s17
	s_waitcnt lgkmcnt(14)
	v_mfma_f32_32x32x16_bf16 v[16:31], v[160:163], v[224:227], v[16:31]
	v_exp_f32_e32 v128, v128
	v_exp_f32_e32 v129, v129
	v_exp_f32_e32 v130, v130
	v_exp_f32_e32 v131, v131
	s_waitcnt lgkmcnt(12)
	v_mfma_f32_32x32x16_bf16 v[32:47], v[160:163], v[112:115], v[32:47]
	v_exp_f32_e32 v132, v132
	v_exp_f32_e32 v133, v133
	v_exp_f32_e32 v134, v134
	v_exp_f32_e32 v135, v135
	v_add_u32_e32 v96, s15, v242
	ds_read_b128 v[80:83], v96
	ds_read_b128 v[104:107], v96 offset:512
	s_waitcnt lgkmcnt(12)
	v_mfma_f32_32x32x16_bf16 v[16:31], v[156:159], v[116:119], v[16:31]
	v_exp_f32_e32 v136, v136
	v_exp_f32_e32 v137, v137
	v_exp_f32_e32 v138, v138
	v_exp_f32_e32 v139, v139
	ds_read_b128 v[108:111], v96 offset:2048
	ds_read_b128 v[176:179], v96 offset:2560
	s_waitcnt lgkmcnt(12)
	v_mfma_f32_32x32x16_bf16 v[32:47], v[156:159], v[84:87], v[32:47]
	v_exp_f32_e32 v140, v140
	v_exp_f32_e32 v141, v141
	v_exp_f32_e32 v142, v142
	v_exp_f32_e32 v143, v143
	ds_read_b128 v[180:183], v96 offset:4096
	ds_read_b128 v[184:187], v96 offset:4608
	s_waitcnt lgkmcnt(12)
	v_mfma_f32_32x32x16_bf16 v[16:31], v[148:151], v[120:123], v[16:31]
	v_exp_f32_e32 v64, v64
	v_exp_f32_e32 v65, v65
	v_exp_f32_e32 v66, v66
	v_exp_f32_e32 v67, v67
	ds_read_b128 v[222:225], v96 offset:6144
	ds_read_b128 v[96:99], v96 offset:6656
	s_waitcnt lgkmcnt(12)
	v_mfma_f32_32x32x16_bf16 v[32:47], v[148:151], v[88:91], v[32:47]
	v_exp_f32_e32 v68, v68
	v_exp_f32_e32 v69, v69
	v_exp_f32_e32 v70, v70
	v_exp_f32_e32 v71, v71
	s_waitcnt lgkmcnt(10)
	v_mfma_f32_32x32x16_bf16 v[16:31], v[144:147], v[100:103], v[16:31]
	v_exp_f32_e32 v72, v72
	v_exp_f32_e32 v73, v73
	v_exp_f32_e32 v74, v74
	v_exp_f32_e32 v75, v75
	s_waitcnt lgkmcnt(8)
	v_mfma_f32_32x32x16_bf16 v[32:47], v[144:147], v[92:95], v[32:47]
	v_exp_f32_e32 v76, v76
	v_exp_f32_e32 v77, v77
	v_exp_f32_e32 v78, v78
	v_exp_f32_e32 v79, v79
	s_waitcnt vmcnt(2) lgkmcnt(0)
	s_barrier
; #define WAIT_BAR(N) asm volatile("s_waitcnt vmcnt(" #N ") lgkmcnt(0)\n\ts_barrier" ::: "memory")
;   #define RESC() do { } while (0)
;   #define ROT() do { sl_prev = sl_cur; sl_cur = sl_next; sl_next = (sl_next == (NSLOT - 1) * SLOTB) ? 0 : sl_next + SLOTB; } while (0)
;   #define ENDW(tt) do { if ((tt) + 3 < NT) { WAIT_BAR(2); } else if ((tt) + 2 < NT) { WAIT_BAR(1); } else { WAIT_BAR(0); } } while (0)
; template <int THRL> __device__ __forceinline__ void attn_unit(const int tid, const float mfix, int q0, int NT, const bf16* Qh, const bf16* __restrict__ Kh, const bf16* __restrict__ Vh, const bf16* Zh, bf16* Oh, const long PQ, const long PO, char* shm) {
;     ...
;   int t = 1;
;   for (; t + 5 < NT; t += 2) {
;     STEP(pB0, pB1, pA0, pA1, t, true, true, true);     WAIT_BAR(2); RESC(); ROT();
;     STEP(pA0, pA1, pB0, pB1, t + 1, true, true, true); WAIT_BAR(2); RESC(); ROT();
;   }
;     ...
;   for (; t + 1 < NT; t += 2) {
;     STEP(pB0, pB1, pA0, pA1, t, (t + 3 < NT), (t + 1 < NT), (t + 1 < NT));         ENDW(t);     RESC(); ROT();
;     STEP(pA0, pA1, pB0, pB1, t + 1, (t + 4 < NT), (t + 2 < NT), (t + 2 < NT));     ENDW(t + 1); RESC(); ROT();
	s_add_i32 s14, s15, 0x2000
	s_cmpk_lg_i32 s15, 0x4000
	s_cselect_b32 s17, s14, 0
	v_add_u32_e32 v219, s23, v244
	ds_read_b64_tr_b16 v[100:101], v219 offset:24576
	ds_read_b64_tr_b16 v[102:103], v219 offset:25088
	v_add_f32_e32 v84, v128, v129
	v_add_f32_e32 v84, v130, v84
	v_add_f32_e32 v84, v131, v84
	v_add_f32_e32 v84, v132, v84
	v_add_f32_e32 v84, v133, v84
	v_cvt_pk_bf16_f32 v160, v128, v129
	v_cvt_pk_bf16_f32 v161, v130, v131
	s_waitcnt lgkmcnt(9)
	v_mfma_f32_32x32x16_bf16 v[112:127], v[80:83], v[172:175], v[48:63]
	ds_read_b64_tr_b16 v[128:129], v219 offset:28672
	ds_read_b64_tr_b16 v[130:131], v219 offset:29184
	v_add_f32_e32 v80, v134, v84
	v_add_f32_e32 v80, v135, v80
	v_add_f32_e32 v80, v136, v80
	v_add_f32_e32 v144, v137, v80
	v_cvt_pk_bf16_f32 v162, v132, v133
	v_cvt_pk_bf16_f32 v163, v134, v135
	s_waitcnt lgkmcnt(10)
	v_mfma_f32_32x32x16_bf16 v[80:95], v[104:107], v[172:175], v[48:63]
	ds_read_b64_tr_b16 v[104:105], v219 offset:25600
	ds_read_b64_tr_b16 v[106:107], v219 offset:26112
	s_waitcnt lgkmcnt(11)
	v_mfma_f32_32x32x16_bf16 v[112:127], v[108:111], v[168:171], v[112:127]
	v_add_f32_e32 v108, v138, v144
	v_add_f32_e32 v108, v139, v108
	v_add_f32_e32 v108, v140, v108
	v_add_f32_e32 v132, v141, v108
	v_cvt_pk_bf16_f32 v156, v136, v137
	v_cvt_pk_bf16_f32 v157, v138, v139
	ds_read_b64_tr_b16 v[108:109], v219 offset:29696
	ds_read_b64_tr_b16 v[110:111], v219 offset:30208
	v_add_f32_e32 v132, v142, v132
	v_add_f32_e32 v132, v143, v132
	v_add_f32_e32 v132, v64, v132
	v_add_f32_e32 v136, v65, v132
	v_cvt_pk_bf16_f32 v158, v140, v141
	v_cvt_pk_bf16_f32 v159, v142, v143
	s_waitcnt lgkmcnt(12)
	v_mfma_f32_32x32x16_bf16 v[80:95], v[176:179], v[168:171], v[80:95]
	ds_read_b64_tr_b16 v[132:133], v219 offset:26624
	ds_read_b64_tr_b16 v[134:135], v219 offset:27136
	v_add_f32_e32 v136, v66, v136
	v_add_f32_e32 v136, v67, v136
	v_add_f32_e32 v136, v68, v136
	v_add_f32_e32 v136, v69, v136
	v_cvt_pk_bf16_f32 v148, v64, v65
	v_cvt_pk_bf16_f32 v149, v66, v67
	s_waitcnt lgkmcnt(13)
	v_mfma_f32_32x32x16_bf16 v[112:127], v[180:183], v[164:167], v[112:127]
	ds_read_b64_tr_b16 v[64:65], v219 offset:30720
	ds_read_b64_tr_b16 v[66:67], v219 offset:31232
	v_add_f32_e32 v136, v70, v136
	v_add_f32_e32 v136, v71, v136
	v_add_f32_e32 v136, v72, v136
	v_add_f32_e32 v136, v73, v136
	v_cvt_pk_bf16_f32 v150, v68, v69
	v_cvt_pk_bf16_f32 v151, v70, v71
	s_waitcnt lgkmcnt(14)
	v_mfma_f32_32x32x16_bf16 v[80:95], v[184:187], v[164:167], v[80:95]
	ds_read_b64_tr_b16 v[68:69], v219 offset:27648
	ds_read_b64_tr_b16 v[70:71], v219 offset:28160
	v_add_f32_e32 v136, v74, v136
	v_add_f32_e32 v136, v75, v136
	v_add_f32_e32 v136, v76, v136
	v_add_f32_e32 v136, v77, v136
	v_cvt_pk_bf16_f32 v144, v72, v73
	v_cvt_pk_bf16_f32 v145, v74, v75
	s_waitcnt lgkmcnt(14)
	v_mfma_f32_32x32x16_bf16 v[112:127], v[222:225], v[152:155], v[112:127]
	ds_read_b64_tr_b16 v[72:73], v219 offset:31744
	ds_read_b64_tr_b16 v[74:75], v219 offset:32256
	v_mfma_f32_32x32x16_bf16 v[80:95], v[96:99], v[152:155], v[80:95]
	v_add_f32_e32 v96, v78, v136
	v_add_f32_e32 v96, v79, v96
	v_add_f32_e32 v96, 0, v96
	v_cvt_pk_bf16_f32 v146, v76, v77
	v_cvt_pk_bf16_f32 v147, v78, v79
	v_lshl_add_u64 v[76:77], v[220:221], 0, s[92:93]
	s_add_i32 s14, s17, s18
	s_mov_b32 s19, m0
	s_mov_b32 m0, s14
	s_nop 0
	global_load_lds_dwordx4 v[76:77], off
	s_mov_b32 m0, s19
	v_add_f32_e32 v188, v188, v96
	s_waitcnt lgkmcnt(14)
	v_mfma_f32_32x32x16_bf16 v[16:31], v[160:163], v[100:103], v[16:31]
	v_exp_f32_e32 v112, v112
	v_exp_f32_e32 v113, v113
	v_exp_f32_e32 v114, v114
	v_exp_f32_e32 v115, v115
	s_waitcnt lgkmcnt(12)
	v_mfma_f32_32x32x16_bf16 v[32:47], v[160:163], v[128:131], v[32:47]
	v_exp_f32_e32 v116, v116
	v_exp_f32_e32 v117, v117
	v_exp_f32_e32 v118, v118
	v_exp_f32_e32 v119, v119
	v_add_u32_e32 v96, s17, v242
	ds_read_b128 v[76:79], v96
	ds_read_b128 v[136:139], v96 offset:512
	s_waitcnt lgkmcnt(12)
	v_mfma_f32_32x32x16_bf16 v[16:31], v[156:159], v[104:107], v[16:31]
	v_exp_f32_e32 v120, v120
	v_exp_f32_e32 v121, v121
	v_exp_f32_e32 v122, v122
	v_exp_f32_e32 v123, v123
	ds_read_b128 v[140:143], v96 offset:2048
	ds_read_b128 v[176:179], v96 offset:2560
	s_waitcnt lgkmcnt(12)
	v_mfma_f32_32x32x16_bf16 v[32:47], v[156:159], v[108:111], v[32:47]
	v_exp_f32_e32 v124, v124
	v_exp_f32_e32 v125, v125
	v_exp_f32_e32 v126, v126
	v_exp_f32_e32 v127, v127
	ds_read_b128 v[180:183], v96 offset:4096
	ds_read_b128 v[184:187], v96 offset:4608
	s_waitcnt lgkmcnt(12)
	v_mfma_f32_32x32x16_bf16 v[16:31], v[148:151], v[132:135], v[16:31]
	v_exp_f32_e32 v80, v80
	v_exp_f32_e32 v81, v81
	v_exp_f32_e32 v82, v82
	v_exp_f32_e32 v83, v83
	ds_read_b128 v[132:135], v96 offset:6144
	ds_read_b128 v[128:131], v96 offset:6656
	s_waitcnt lgkmcnt(12)
	v_mfma_f32_32x32x16_bf16 v[32:47], v[148:151], v[64:67], v[32:47]
	v_exp_f32_e32 v84, v84
	v_exp_f32_e32 v85, v85
	v_exp_f32_e32 v86, v86
	v_exp_f32_e32 v87, v87
	s_waitcnt lgkmcnt(10)
	v_mfma_f32_32x32x16_bf16 v[16:31], v[144:147], v[68:71], v[16:31]
	v_exp_f32_e32 v88, v88
	v_exp_f32_e32 v89, v89
	v_exp_f32_e32 v90, v90
	v_exp_f32_e32 v91, v91
	s_waitcnt lgkmcnt(8)
	v_mfma_f32_32x32x16_bf16 v[32:47], v[144:147], v[72:75], v[32:47]
	v_exp_f32_e32 v92, v92
	v_exp_f32_e32 v93, v93
	v_exp_f32_e32 v94, v94
	v_exp_f32_e32 v95, v95
	s_waitcnt vmcnt(1) lgkmcnt(0)
	s_barrier
; #define WAIT_BAR(N) asm volatile("s_waitcnt vmcnt(" #N ") lgkmcnt(0)\n\ts_barrier" ::: "memory")
;   #define RESC() do { } while (0)
;   #define ROT() do { sl_prev = sl_cur; sl_cur = sl_next; sl_next = (sl_next == (NSLOT - 1) * SLOTB) ? 0 : sl_next + SLOTB; } while (0)
;   #define ENDW(tt) do { if ((tt) + 3 < NT) { WAIT_BAR(2); } else if ((tt) + 2 < NT) { WAIT_BAR(1); } else { WAIT_BAR(0); } } while (0)
; template <int THRL> __device__ __forceinline__ void attn_unit(const int tid, const float mfix, int q0, int NT, const bf16* Qh, const bf16* __restrict__ Kh, const bf16* __restrict__ Vh, const bf16* Zh, bf16* Oh, const long PQ, const long PO, char* shm) {
;     ...
;   int t = 1;
;   for (; t + 5 < NT; t += 2) {
;     STEP(pB0, pB1, pA0, pA1, t, true, true, true);     WAIT_BAR(2); RESC(); ROT();
;     STEP(pA0, pA1, pB0, pB1, t + 1, true, true, true); WAIT_BAR(2); RESC(); ROT();
;   }
;     ...
;   for (; t + 1 < NT; t += 2) {
;     STEP(pB0, pB1, pA0, pA1, t, (t + 3 < NT), (t + 1 < NT), (t + 1 < NT));         ENDW(t);     RESC(); ROT();
;     STEP(pA0, pA1, pB0, pB1, t + 1, (t + 4 < NT), (t + 2 < NT), (t + 2 < NT));     ENDW(t + 1); RESC(); ROT();
	s_add_i32 s14, s17, 0x2000
	s_cmpk_lg_i32 s17, 0x4000
	s_cselect_b32 s14, s14, 0
	v_add_u32_e32 v219, s15, v244
	ds_read_b64_tr_b16 v[222:223], v219 offset:24576
	ds_read_b64_tr_b16 v[224:225], v219 offset:25088
	v_add_f32_e32 v64, v112, v113
	v_add_f32_e32 v64, v114, v64
	v_add_f32_e32 v64, v115, v64
	v_add_f32_e32 v64, v116, v64
	v_add_f32_e32 v64, v117, v64
	v_cvt_pk_bf16_f32 v160, v112, v113
	v_cvt_pk_bf16_f32 v161, v114, v115
	s_waitcnt lgkmcnt(9)
	v_mfma_f32_32x32x16_bf16 v[96:111], v[76:79], v[172:175], v[48:63]
	ds_read_b64_tr_b16 v[112:113], v219 offset:28672
	ds_read_b64_tr_b16 v[114:115], v219 offset:29184
	v_add_f32_e32 v64, v118, v64
	v_add_f32_e32 v64, v119, v64
	v_add_f32_e32 v64, v120, v64
	v_add_f32_e32 v144, v121, v64
	s_waitcnt lgkmcnt(10)
	v_mfma_f32_32x32x16_bf16 v[64:79], v[136:139], v[172:175], v[48:63]
	v_cvt_pk_bf16_f32 v162, v116, v117
	v_cvt_pk_bf16_f32 v163, v118, v119
	ds_read_b64_tr_b16 v[136:137], v219 offset:25600
	ds_read_b64_tr_b16 v[138:139], v219 offset:26112
	v_add_f32_e32 v116, v122, v144
	v_add_f32_e32 v116, v123, v116
	v_add_f32_e32 v116, v124, v116
	v_add_f32_e32 v116, v125, v116
	v_cvt_pk_bf16_f32 v156, v120, v121
	v_cvt_pk_bf16_f32 v157, v122, v123
	s_waitcnt lgkmcnt(11)
	v_mfma_f32_32x32x16_bf16 v[96:111], v[140:143], v[168:171], v[96:111]
	ds_read_b64_tr_b16 v[118:119], v219 offset:29696
	ds_read_b64_tr_b16 v[120:121], v219 offset:30208
	s_waitcnt lgkmcnt(12)
	v_mfma_f32_32x32x16_bf16 v[64:79], v[176:179], v[168:171], v[64:79]
	v_add_f32_e32 v116, v126, v116
	v_add_f32_e32 v116, v127, v116
	v_add_f32_e32 v116, v80, v116
	v_add_f32_e32 v116, v81, v116
	v_cvt_pk_bf16_f32 v158, v124, v125
	v_cvt_pk_bf16_f32 v159, v126, v127
	ds_read_b64_tr_b16 v[122:123], v219 offset:26624
	ds_read_b64_tr_b16 v[124:125], v219 offset:27136
	v_add_f32_e32 v116, v82, v116
	v_add_f32_e32 v116, v83, v116
	v_add_f32_e32 v116, v84, v116
	v_add_f32_e32 v116, v85, v116
	v_cvt_pk_bf16_f32 v148, v80, v81
	v_cvt_pk_bf16_f32 v149, v82, v83
	s_waitcnt lgkmcnt(13)
	v_mfma_f32_32x32x16_bf16 v[96:111], v[180:183], v[164:167], v[96:111]
	ds_read_b64_tr_b16 v[80:81], v219 offset:30720
	ds_read_b64_tr_b16 v[82:83], v219 offset:31232
	s_waitcnt lgkmcnt(14)
	v_mfma_f32_32x32x16_bf16 v[64:79], v[184:187], v[164:167], v[64:79]
	v_add_f32_e32 v116, v86, v116
	v_add_f32_e32 v116, v87, v116
	v_add_f32_e32 v116, v88, v116
	v_add_f32_e32 v116, v89, v116
	v_cvt_pk_bf16_f32 v150, v84, v85
	v_cvt_pk_bf16_f32 v151, v86, v87
	ds_read_b64_tr_b16 v[84:85], v219 offset:27648
	ds_read_b64_tr_b16 v[86:87], v219 offset:28160
	v_add_f32_e32 v116, v90, v116
	v_add_f32_e32 v116, v91, v116
	v_add_f32_e32 v116, v92, v116
	v_add_f32_e32 v116, v93, v116
	v_cvt_pk_bf16_f32 v144, v88, v89
	v_cvt_pk_bf16_f32 v145, v90, v91
	s_waitcnt lgkmcnt(14)
	v_mfma_f32_32x32x16_bf16 v[96:111], v[132:135], v[152:155], v[96:111]
	ds_read_b64_tr_b16 v[88:89], v219 offset:31744
	ds_read_b64_tr_b16 v[90:91], v219 offset:32256
	v_mfma_f32_32x32x16_bf16 v[64:79], v[128:131], v[152:155], v[64:79]
	v_add_f32_e32 v116, v94, v116
	v_add_f32_e32 v116, v95, v116
	v_add_f32_e32 v116, 0, v116
	v_cvt_pk_bf16_f32 v146, v92, v93
	v_cvt_pk_bf16_f32 v147, v94, v95
	s_add_i32 s15, s14, s18
	v_lshl_add_u64 v[92:93], v[220:221], 0, s[94:95]
	s_mov_b32 s18, m0
	s_mov_b32 m0, s15
	s_nop 0
	global_load_lds_dwordx4 v[92:93], off
	s_mov_b32 m0, s18
	v_add_f32_e32 v116, v188, v116
	s_waitcnt lgkmcnt(14)
	v_mfma_f32_32x32x16_bf16 v[16:31], v[160:163], v[222:225], v[16:31]
	v_exp_f32_e32 v96, v96
	v_exp_f32_e32 v97, v97
	v_exp_f32_e32 v98, v98
	v_exp_f32_e32 v99, v99
	s_waitcnt lgkmcnt(12)
	v_mfma_f32_32x32x16_bf16 v[32:47], v[160:163], v[112:115], v[32:47]
	v_exp_f32_e32 v100, v100
	v_exp_f32_e32 v101, v101
	v_exp_f32_e32 v102, v102
	v_exp_f32_e32 v103, v103
	v_add_u32_e32 v92, s14, v242
	ds_read_b128 v[126:129], v92
	ds_read_b128 v[130:133], v92 offset:512
	s_waitcnt lgkmcnt(12)
	v_mfma_f32_32x32x16_bf16 v[16:31], v[156:159], v[136:139], v[16:31]
	v_exp_f32_e32 v104, v104
	v_exp_f32_e32 v105, v105
	v_exp_f32_e32 v106, v106
	v_exp_f32_e32 v107, v107
	ds_read_b128 v[134:137], v92 offset:2048
	ds_read_b128 v[138:141], v92 offset:2560
	s_waitcnt lgkmcnt(12)
	v_mfma_f32_32x32x16_bf16 v[32:47], v[156:159], v[118:121], v[32:47]
	v_exp_f32_e32 v108, v108
	v_exp_f32_e32 v109, v109
	v_exp_f32_e32 v110, v110
	v_exp_f32_e32 v111, v111
	ds_read_b128 v[118:121], v92 offset:4096
	ds_read_b128 v[176:179], v92 offset:4608
	s_waitcnt lgkmcnt(12)
	v_mfma_f32_32x32x16_bf16 v[16:31], v[148:151], v[122:125], v[16:31]
	v_exp_f32_e32 v64, v64
	v_exp_f32_e32 v65, v65
	v_exp_f32_e32 v66, v66
	v_exp_f32_e32 v67, v67
	ds_read_b128 v[122:125], v92 offset:6144
	ds_read_b128 v[112:115], v92 offset:6656
	s_waitcnt lgkmcnt(12)
	v_mfma_f32_32x32x16_bf16 v[32:47], v[148:151], v[80:83], v[32:47]
	v_exp_f32_e32 v68, v68
	v_exp_f32_e32 v69, v69
	v_exp_f32_e32 v70, v70
	v_exp_f32_e32 v71, v71
	s_waitcnt lgkmcnt(10)
	v_mfma_f32_32x32x16_bf16 v[16:31], v[144:147], v[84:87], v[16:31]
	v_exp_f32_e32 v72, v72
	v_exp_f32_e32 v73, v73
	v_exp_f32_e32 v74, v74
	v_exp_f32_e32 v75, v75
	s_waitcnt lgkmcnt(8)
	v_mfma_f32_32x32x16_bf16 v[32:47], v[144:147], v[88:91], v[32:47]
	v_exp_f32_e32 v76, v76
	v_exp_f32_e32 v77, v77
	v_exp_f32_e32 v78, v78
	v_exp_f32_e32 v79, v79
	s_waitcnt vmcnt(0) lgkmcnt(0)
	s_barrier
; #define WAIT_BAR(N) asm volatile("s_waitcnt vmcnt(" #N ") lgkmcnt(0)\n\ts_barrier" ::: "memory")
;   #define RESC() do { } while (0)
;   #define ROT() do { sl_prev = sl_cur; sl_cur = sl_next; sl_next = (sl_next == (NSLOT - 1) * SLOTB) ? 0 : sl_next + SLOTB; } while (0)
;   #define ENDW(tt) do { if ((tt) + 3 < NT) { WAIT_BAR(2); } else if ((tt) + 2 < NT) { WAIT_BAR(1); } else { WAIT_BAR(0); } } while (0)
; template <int THRL> __device__ __forceinline__ void attn_unit(const int tid, const float mfix, int q0, int NT, const bf16* Qh, const bf16* __restrict__ Kh, const bf16* __restrict__ Vh, const bf16* Zh, bf16* Oh, const long PQ, const long PO, char* shm) {
;     ...
;   int t = 1;
;   for (; t + 5 < NT; t += 2) {
;     STEP(pB0, pB1, pA0, pA1, t, true, true, true);     WAIT_BAR(2); RESC(); ROT();
;     STEP(pA0, pA1, pB0, pB1, t + 1, true, true, true); WAIT_BAR(2); RESC(); ROT();
;   }
;     ...
;   for (; t + 1 < NT; t += 2) {
;     STEP(pB0, pB1, pA0, pA1, t, (t + 3 < NT), (t + 1 < NT), (t + 1 < NT));         ENDW(t);     RESC(); ROT();
;     STEP(pA0, pA1, pB0, pB1, t + 1, (t + 4 < NT), (t + 2 < NT), (t + 2 < NT));     ENDW(t + 1); RESC(); ROT();
;   }
;   STEP(pB0, pB1, pA0, pA1, NT - 1, false, false, false); RESC();
	v_add_u32_e32 v117, s17, v244
	ds_read_b64_tr_b16 v[180:181], v117 offset:24576
	ds_read_b64_tr_b16 v[182:183], v117 offset:25088
	v_add_f32_e32 v80, v96, v97
	v_add_f32_e32 v80, v98, v80
	v_add_f32_e32 v80, v99, v80
	v_add_f32_e32 v80, v100, v80
	v_add_f32_e32 v142, v101, v80
	v_cvt_pk_bf16_f32 v160, v96, v97
	v_cvt_pk_bf16_f32 v161, v98, v99
	s_waitcnt lgkmcnt(9)
	v_mfma_f32_32x32x16_bf16 v[80:95], v[126:129], v[172:175], v[48:63]
	ds_read_b64_tr_b16 v[96:97], v117 offset:28672
	ds_read_b64_tr_b16 v[98:99], v117 offset:29184
	s_waitcnt lgkmcnt(10)
	v_mfma_f32_32x32x16_bf16 v[48:63], v[130:133], v[172:175], v[48:63]
	v_add_f32_e32 v126, v102, v142
	v_add_f32_e32 v126, v103, v126
	v_add_f32_e32 v126, v104, v126
	v_add_f32_e32 v126, v105, v126
	v_cvt_pk_bf16_f32 v162, v100, v101
	v_cvt_pk_bf16_f32 v163, v102, v103
	ds_read_b64_tr_b16 v[100:101], v117 offset:25600
	ds_read_b64_tr_b16 v[102:103], v117 offset:26112
	v_add_f32_e32 v126, v106, v126
	v_add_f32_e32 v126, v107, v126
	v_add_f32_e32 v126, v108, v126
	v_add_f32_e32 v126, v109, v126
	v_cvt_pk_bf16_f32 v156, v104, v105
	v_cvt_pk_bf16_f32 v157, v106, v107
	s_waitcnt lgkmcnt(11)
	v_mfma_f32_32x32x16_bf16 v[80:95], v[134:137], v[168:171], v[80:95]
	ds_read_b64_tr_b16 v[104:105], v117 offset:29696
	ds_read_b64_tr_b16 v[106:107], v117 offset:30208
	s_waitcnt lgkmcnt(12)
	v_mfma_f32_32x32x16_bf16 v[48:63], v[138:141], v[168:171], v[48:63]
	v_add_f32_e32 v126, v110, v126
	v_add_f32_e32 v126, v111, v126
	v_add_f32_e32 v126, v64, v126
	v_add_f32_e32 v126, v65, v126
	v_cvt_pk_bf16_f32 v158, v108, v109
	v_cvt_pk_bf16_f32 v159, v110, v111
	ds_read_b64_tr_b16 v[108:109], v117 offset:26624
	ds_read_b64_tr_b16 v[110:111], v117 offset:27136
	s_waitcnt lgkmcnt(13)
	v_mfma_f32_32x32x16_bf16 v[80:95], v[118:121], v[164:167], v[80:95]
	v_add_f32_e32 v118, v66, v126
	v_add_f32_e32 v118, v67, v118
	v_add_f32_e32 v118, v68, v118
	v_add_f32_e32 v118, v69, v118
	v_cvt_pk_bf16_f32 v148, v64, v65
	v_cvt_pk_bf16_f32 v149, v66, v67
	ds_read_b64_tr_b16 v[64:65], v117 offset:30720
	ds_read_b64_tr_b16 v[66:67], v117 offset:31232
	s_waitcnt lgkmcnt(14)
	v_mfma_f32_32x32x16_bf16 v[48:63], v[176:179], v[164:167], v[48:63]
	v_add_f32_e32 v118, v70, v118
	v_add_f32_e32 v118, v71, v118
	v_add_f32_e32 v118, v72, v118
	v_add_f32_e32 v118, v73, v118
	v_cvt_pk_bf16_f32 v150, v68, v69
	v_cvt_pk_bf16_f32 v151, v70, v71
	ds_read_b64_tr_b16 v[68:69], v117 offset:27648
	ds_read_b64_tr_b16 v[70:71], v117 offset:28160
	v_add_f32_e32 v118, v74, v118
	v_add_f32_e32 v118, v75, v118
	v_add_f32_e32 v118, v76, v118
	v_add_f32_e32 v118, v77, v118
	v_cvt_pk_bf16_f32 v144, v72, v73
	v_cvt_pk_bf16_f32 v145, v74, v75
	s_waitcnt lgkmcnt(14)
	v_mfma_f32_32x32x16_bf16 v[80:95], v[122:125], v[152:155], v[80:95]
	ds_read_b64_tr_b16 v[72:73], v117 offset:31744
	ds_read_b64_tr_b16 v[74:75], v117 offset:32256
	v_mfma_f32_32x32x16_bf16 v[48:63], v[112:115], v[152:155], v[48:63]
	v_add_f32_e32 v112, v78, v118
	v_add_f32_e32 v112, v79, v112
	v_add_f32_e32 v112, 0, v112
	v_cvt_pk_bf16_f32 v146, v76, v77
	v_cvt_pk_bf16_f32 v147, v78, v79
	s_waitcnt lgkmcnt(14)
	v_mfma_f32_32x32x16_bf16 v[16:31], v[160:163], v[180:183], v[16:31]
	s_nop 1
	v_exp_f32_e32 v80, v80
	v_exp_f32_e32 v81, v81
	v_exp_f32_e32 v82, v82
	v_exp_f32_e32 v83, v83
	s_waitcnt lgkmcnt(12)
	v_mfma_f32_32x32x16_bf16 v[32:47], v[160:163], v[96:99], v[32:47]
	v_exp_f32_e32 v84, v84
	v_exp_f32_e32 v85, v85
	v_exp_f32_e32 v86, v86
	v_exp_f32_e32 v87, v87
	s_waitcnt lgkmcnt(10)
	v_mfma_f32_32x32x16_bf16 v[16:31], v[156:159], v[100:103], v[16:31]
	v_exp_f32_e32 v88, v88
	v_exp_f32_e32 v89, v89
	v_exp_f32_e32 v90, v90
	v_exp_f32_e32 v91, v91
	s_waitcnt lgkmcnt(8)
	v_mfma_f32_32x32x16_bf16 v[32:47], v[156:159], v[104:107], v[32:47]
	v_exp_f32_e32 v92, v92
	v_exp_f32_e32 v93, v93
	v_exp_f32_e32 v94, v94
	v_exp_f32_e32 v95, v95
	s_waitcnt lgkmcnt(6)
; #define SBAR() __builtin_amdgcn_sched_barrier(0)
; #define WAIT_BAR(N) asm volatile("s_waitcnt vmcnt(" #N ") lgkmcnt(0)\n\ts_barrier" ::: "memory")
;   #define RESC() do { } while (0)
;   #define ROT() do { sl_prev = sl_cur; sl_cur = sl_next; sl_next = (sl_next == (NSLOT - 1) * SLOTB) ? 0 : sl_next + SLOTB; } while (0)
;   #define PKW(P, B) cvtpk_s(P[B], P[B + 1])
;   #define ENDW(tt) do { if ((tt) + 3 < NT) { WAIT_BAR(2); } else if ((tt) + 2 < NT) { WAIT_BAR(1); } else { WAIT_BAR(0); } } while (0)
; template <int THRL> __device__ __forceinline__ void attn_unit(const int tid, const float mfix, int q0, int NT, const bf16* Qh, const bf16* __restrict__ Kh, const bf16* __restrict__ Vh, const bf16* Zh, bf16* Oh, const long PQ, const long PO, char* shm) {
;     ...
;   int t = 1;
;   for (; t + 5 < NT; t += 2) {
;     STEP(pB0, pB1, pA0, pA1, t, true, true, true);     WAIT_BAR(2); RESC(); ROT();
;     STEP(pA0, pA1, pB0, pB1, t + 1, true, true, true); WAIT_BAR(2); RESC(); ROT();
;   }
;     ...
;   for (; t + 1 < NT; t += 2) {
;     STEP(pB0, pB1, pA0, pA1, t, (t + 3 < NT), (t + 1 < NT), (t + 1 < NT));         ENDW(t);     RESC(); ROT();
;     STEP(pA0, pA1, pB0, pB1, t + 1, (t + 4 < NT), (t + 2 < NT), (t + 2 < NT));     ENDW(t + 1); RESC(); ROT();
;   }
;   STEP(pB0, pB1, pA0, pA1, NT - 1, false, false, false); RESC();
;   { float sacc = pB0[0] + pB0[1]; _Pragma("unroll") for (int r = 2; r < 16; ++r) sacc += pB0[r]; _Pragma("unroll") for (int r = 0; r < 16; ++r) sacc += pB1[r]; l_reg += sacc;
;     pw0 = (u32x4){PKW(pB0, 0), PKW(pB0, 2), PKW(pB0, 4), PKW(pB0, 6)}; pw1 = (u32x4){PKW(pB0, 8), PKW(pB0, 10), PKW(pB0, 12), PKW(pB0, 14)}; pw2 = (u32x4){PKW(pB1, 0), PKW(pB1, 2), PKW(pB1, 4), PKW(pB1, 6)}; pw3 = (u32x4){PKW(pB1, 8), PKW(pB1, 10), PKW(pB1, 12), PKW(pB1, 14)};
;     SBAR(); pv(o, vb0 + sl_cur, PAF(0), PAF(1), PAF(2), PAF(3)); }
;     ...
;   { auto rr = __builtin_amdgcn_permlane32_swap(__float_as_uint(l_reg), __float_as_uint(l_reg), false, false); l_reg = __uint_as_float(rr[0]) + __uint_as_float(rr[1]); }
;   if (hi == 0) wsf[32 + r32] = l_reg; asm volatile("s_waitcnt lgkmcnt(0)" ::: "memory");
	v_mfma_f32_32x32x16_bf16 v[16:31], v[148:151], v[108:111], v[16:31]
	v_exp_f32_e32 v48, v48
	v_exp_f32_e32 v49, v49
	v_exp_f32_e32 v50, v50
	v_exp_f32_e32 v51, v51
	s_waitcnt lgkmcnt(4)
	v_mfma_f32_32x32x16_bf16 v[32:47], v[148:151], v[64:67], v[32:47]
	v_exp_f32_e32 v52, v52
	v_exp_f32_e32 v53, v53
	v_exp_f32_e32 v54, v54
	v_exp_f32_e32 v55, v55
	s_waitcnt lgkmcnt(2)
	v_mfma_f32_32x32x16_bf16 v[16:31], v[144:147], v[68:71], v[16:31]
	v_exp_f32_e32 v56, v56
	v_exp_f32_e32 v57, v57
	v_exp_f32_e32 v58, v58
	v_exp_f32_e32 v59, v59
	s_waitcnt lgkmcnt(0)
	v_mfma_f32_32x32x16_bf16 v[32:47], v[144:147], v[72:75], v[32:47]
	v_exp_f32_e32 v60, v60
	v_exp_f32_e32 v61, v61
	v_exp_f32_e32 v62, v62
	v_exp_f32_e32 v63, v63
	v_add_f32_e32 v64, v80, v81
	v_add_f32_e32 v64, v82, v64
	v_add_f32_e32 v64, v83, v64
	v_add_f32_e32 v64, v84, v64
	v_add_f32_e32 v64, v85, v64
	v_add_f32_e32 v64, v86, v64
	v_add_f32_e32 v64, v87, v64
	v_add_f32_e32 v64, v88, v64
	v_add_f32_e32 v64, v89, v64
	v_add_f32_e32 v64, v90, v64
	v_add_f32_e32 v64, v91, v64
	v_add_f32_e32 v64, v92, v64
	v_add_f32_e32 v64, v93, v64
	v_add_f32_e32 v64, v94, v64
	v_add_f32_e32 v64, v95, v64
	v_add_f32_e32 v64, v48, v64
	v_add_f32_e32 v64, v49, v64
	v_add_f32_e32 v64, v50, v64
	v_add_f32_e32 v64, v51, v64
	v_add_f32_e32 v64, v52, v64
	v_add_f32_e32 v64, v53, v64
	v_add_f32_e32 v64, v54, v64
	v_add_f32_e32 v64, v55, v64
	v_add_f32_e32 v64, v56, v64
	v_add_f32_e32 v64, v57, v64
	v_add_f32_e32 v64, v58, v64
	v_add_f32_e32 v64, v59, v64
	v_add_f32_e32 v64, v60, v64
	v_add_f32_e32 v64, v61, v64
	v_add_f32_e32 v64, v62, v64
	v_add_f32_e32 v64, v63, v64
	v_add_f32_e32 v65, v116, v112
	v_add_f32_e32 v64, v65, v64
	v_cvt_pk_bf16_f32 v48, v48, v49
	v_cvt_pk_bf16_f32 v66, v80, v81
	v_cvt_pk_bf16_f32 v67, v82, v83
	v_cvt_pk_bf16_f32 v68, v84, v85
	v_cvt_pk_bf16_f32 v69, v86, v87
	v_cvt_pk_bf16_f32 v70, v88, v89
	v_cvt_pk_bf16_f32 v71, v90, v91
	v_cvt_pk_bf16_f32 v72, v92, v93
	v_cvt_pk_bf16_f32 v73, v94, v95
	v_cvt_pk_bf16_f32 v49, v50, v51
	v_cvt_pk_bf16_f32 v50, v52, v53
	v_cvt_pk_bf16_f32 v51, v54, v55
	v_cvt_pk_bf16_f32 v52, v56, v57
	v_cvt_pk_bf16_f32 v53, v58, v59
	v_cvt_pk_bf16_f32 v54, v60, v61
	v_cvt_pk_bf16_f32 v55, v62, v63
	v_add_u32_e32 v65, s14, v243
	ds_read_b64_tr_b16 v[56:57],v65 offset:0
	ds_read_b64_tr_b16 v[58:59],v65 offset:512
	ds_read_b64_tr_b16 v[60:61],v65 offset:1024
	ds_read_b64_tr_b16 v[62:63],v65 offset:1536
	ds_read_b64_tr_b16 v[74:75],v65 offset:2048
	ds_read_b64_tr_b16 v[76:77],v65 offset:2560
	ds_read_b64_tr_b16 v[78:79],v65 offset:3072
	ds_read_b64_tr_b16 v[80:81],v65 offset:3584
	s_waitcnt lgkmcnt(0)
	s_nop 0
	v_mfma_f32_32x32x16_bf16 v[16:31], v[66:69], v[56:59], v[16:31]
	ds_read_b64_tr_b16 v[56:57],v65 offset:4096
	ds_read_b64_tr_b16 v[58:59],v65 offset:4608
	v_mfma_f32_32x32x16_bf16 v[16:31], v[70:73], v[60:63], v[16:31]
	ds_read_b64_tr_b16 v[60:61],v65 offset:5120
	ds_read_b64_tr_b16 v[62:63],v65 offset:5632
	v_mfma_f32_32x32x16_bf16 v[16:31], v[48:51], v[74:77], v[16:31]
	ds_read_b64_tr_b16 v[74:75],v65 offset:6144
	ds_read_b64_tr_b16 v[76:77],v65 offset:6656
	v_mfma_f32_32x32x16_bf16 v[16:31], v[52:55], v[78:81], v[16:31]
	ds_read_b64_tr_b16 v[78:79],v65 offset:7168
	ds_read_b64_tr_b16 v[80:81],v65 offset:7680
	s_waitcnt lgkmcnt(0)
	v_mfma_f32_32x32x16_bf16 v[32:47], v[66:69], v[56:59], v[32:47]
	v_mfma_f32_32x32x16_bf16 v[32:47], v[70:73], v[60:63], v[32:47]
	v_mfma_f32_32x32x16_bf16 v[32:47], v[48:51], v[74:77], v[32:47]
	v_mov_b32_e32 v48, v64
	s_nop 1
	v_permlane32_swap_b32_e32 v64, v48
	v_mfma_f32_32x32x16_bf16 v[32:47], v[52:55], v[78:81], v[32:47]
	s_and_saveexec_b64 s[14:15], s[4:5]
	s_cbranch_execz .LBB0_386
	v_add_f32_e32 v48, v64, v48
	v_lshl_add_u32 v49, v239, 2, s16
	ds_write_b32 v49, v48 offset:49280
	s_branch .LBB0_386
